# MoE up-projection: the eight gathered-row ids of a block's first tile are loaded together instead of one exposed round trip each
# baseline (speedup 1.0000x reference)
; DI void moe_e1_phase(const Params& P, int l, char* smem, int* tb) {
;     ...
;   auto setup = [&](int rt, int nt, int (&tok)[8], const half_t*& w1, const half_t*& w3) {
;     int e = 0;
;     while (tb[e + 1] <= rt) e++;
;     const int rl = rt - tb[e], cnt = P.cnt[l * 32 + e];
;     const int* lst = P.list + (size_t)e * LCAP;
;     w1 = P.Wt1 + ((size_t)(l * 32 + e) * 512 + nt * 64) * 1024 + sc;
;     w3 = P.Wt3 + ((size_t)(l * 32 + e) * 512 + nt * 64) * 1024 + sc;
; #pragma unroll
;     for (int i = 0; i < 8; i++) tok[i] = lst[min(rl * 256 + i * 32 + srow, cnt - 1)] >> 1;
;   };
.LBB0_566:
	v_readlane_b32 s2, v255, 26
	s_lshl_b32 s23, s2, 5
	v_readlane_b32 s3, v255, 27
	s_add_i32 s84, s0, s23
	s_lshl_b64 s[2:3], s[84:85], 2
	v_readlane_b32 s4, v253, 63
	v_readlane_b32 s5, v255, 0
	s_add_u32 s2, s4, s2
	s_addc_u32 s3, s5, s3
	s_lshl_b32 s2, s0, 2
	s_add_i32 s2, s2, 0x24000
	v_mov_b32_e32 v3, s2
	ds_read_b32 v3, v3
	v_mov_b32_e32 v2, s1
	ds_read_b32 v2, v2
	v_ashrrev_i32_e32 v24, 3, v16
	s_mul_hi_u32 s1, s0, 0x84000
	s_mul_i32 s0, s0, 0x84000
	v_readlane_b32 s2, v255, 24
	s_waitcnt lgkmcnt(0)
	v_sub_u32_e32 v2, s21, v2
	v_lshlrev_b32_e32 v4, 8, v2
	v_add_u32_e32 v2, v4, v24
	v_readlane_b32 s3, v255, 25
	s_add_u32 s0, s2, s0
	s_addc_u32 s1, s3, s1
	v_add_u32_e32 v26, 32, v24
	v_add_u32_e32 v78, 64, v24
	v_add_u32_e32 v79, 0x60, v24
	v_add_u32_e32 v80, 0x80, v24
	v_add_u32_e32 v81, 0xa0, v24
	v_add_u32_e32 v82, 0xc0, v24
	v_add_u32_e32 v83, 0xe0, v24
	s_lshl_b32 s2, s22, 6
	v_lshrrev_b32_e32 v54, 4, v1
	s_ashr_i32 s3, s2, 31
	s_lshl_b64 s[4:5], s[84:85], 20
	v_readlane_b32 s6, v253, 53
	v_xor_b32_e32 v0, v54, v1
	s_add_u32 s6, s6, s4
	v_readlane_b32 s7, v253, 54
	v_lshlrev_b32_e32 v0, 3, v0
	s_addc_u32 s7, s7, s5
	s_lshl_b64 s[2:3], s[2:3], 11
	v_and_b32_e32 v0, 56, v0
	s_add_u32 s6, s6, s2
	s_addc_u32 s7, s7, s3
	v_lshlrev_b32_e32 v148, 1, v0
	v_lshl_add_u64 v[28:29], s[6:7], 0, v[148:149]
	v_readlane_b32 s6, v253, 55
	s_add_u32 s4, s6, s4
	v_readlane_b32 s6, v253, 56
	s_addc_u32 s5, s6, s5
	s_add_u32 s2, s4, s2
	s_addc_u32 s3, s5, s3
	v_lshl_add_u64 v[30:31], s[2:3], 0, v[148:149]
	v_readlane_b32 s2, v255, 58
	v_readlane_b32 s3, v255, 59
	v_ashrrev_i32_e32 v25, 31, v24
	v_lshlrev_b64 v[48:49], 11, v[24:25]
	v_ashrrev_i32_e32 v27, 31, v26
	v_lshlrev_b64 v[50:51], 11, v[26:27]
	v_lshl_add_u64 v[56:57], v[30:31], 0, v[50:51]
	v_bitop3_b32 v1, v54, 7, v1 bitop3:0x48
	s_waitcnt lgkmcnt(0)
	v_add_u32_e32 v5, -1, v3
	v_min_i32_e32 v2, v2, v5
	v_ashrrev_i32_e32 v3, 31, v2
	v_lshl_add_u64 v[2:3], v[2:3], 2, s[0:1]
	global_load_dword v200, v[2:3], off
	v_add_u32_e32 v2, v4, v26
	v_min_i32_e32 v2, v2, v5
	v_ashrrev_i32_e32 v3, 31, v2
	v_lshl_add_u64 v[2:3], v[2:3], 2, s[0:1]
	global_load_dword v201, v[2:3], off
	v_add_u32_e32 v2, v4, v78
	v_min_i32_e32 v2, v2, v5
	v_ashrrev_i32_e32 v3, 31, v2
	v_lshl_add_u64 v[2:3], v[2:3], 2, s[0:1]
	global_load_dword v202, v[2:3], off
	v_add_u32_e32 v2, v4, v79
	v_min_i32_e32 v2, v2, v5
	v_ashrrev_i32_e32 v3, 31, v2
	v_lshl_add_u64 v[2:3], v[2:3], 2, s[0:1]
	global_load_dword v203, v[2:3], off
	v_add_u32_e32 v2, v4, v80
	v_min_i32_e32 v2, v2, v5
	v_ashrrev_i32_e32 v3, 31, v2
	v_lshl_add_u64 v[2:3], v[2:3], 2, s[0:1]
	global_load_dword v204, v[2:3], off
	v_add_u32_e32 v2, v4, v81
	v_min_i32_e32 v2, v2, v5
	v_ashrrev_i32_e32 v3, 31, v2
	v_lshl_add_u64 v[2:3], v[2:3], 2, s[0:1]
	global_load_dword v205, v[2:3], off
	v_add_u32_e32 v2, v4, v82
	v_min_i32_e32 v2, v2, v5
	v_ashrrev_i32_e32 v3, 31, v2
	v_lshl_add_u64 v[2:3], v[2:3], 2, s[0:1]
	global_load_dword v206, v[2:3], off
	v_add_u32_e32 v2, v4, v83
	v_min_i32_e32 v2, v2, v5
	v_ashrrev_i32_e32 v3, 31, v2
	v_lshl_add_u64 v[2:3], v[2:3], 2, s[0:1]
	global_load_dword v207, v[2:3], off
	s_waitcnt vmcnt(0)
; #define TIDX tid_opaque()
; template <class AF, class BF>
; DI void gemm_prologue(AF aptr, BF bptr, int nk, char* smem) {
;   const int tid = TIDX;
; #pragma unroll
;   for (int st = 0; st < 2; st++) {
;     if (st < nk) {
;       char* d = smem + st * 49152 + tid * 16;
; #pragma unroll
;       for (int i = 0; i < 8; i++) glds16(aptr(i) + st * 64, d + i * 4096);
; #pragma unroll
;       for (int i = 0; i < 4; i++) glds16(bptr(i) + st * 64, d + 32768 + i * 4096);
;     }
;   }
; DI void moe_e1_phase(const Params& P, int l, char* smem, int* tb) {
;     ...
;     for (int i = 0; i < 8; i++) tok[i] = lst[min(rl * 256 + i * 32 + srow, cnt - 1)] >> 1;
;   };
;   int it = 0, rt, nt;
;   bool have = next_tile(it, MT, 8, rt, nt);
;   int tok[8]; const half_t* w1 = nullptr; const half_t* w3 = nullptr;
;   if (have) {
;     asm volatile("" : "+s"(rt), "+s"(nt));
;     setup(rt, nt, tok, w1, w3);
;     gemm_prologue([&](int i) { return P.hx + (size_t)tok[i] * D + sc; }, [&](int i) { return ((i & 1) ? w3 : w1) + (size_t)((i >> 1) * 32 + srow) * 1024; }, 16, smem);
	v_ashrrev_i32_e32 v32, 1, v200
	v_ashrrev_i32_e32 v34, 1, v201
	v_ashrrev_i32_e32 v36, 1, v202
	v_ashrrev_i32_e32 v38, 1, v203
	v_ashrrev_i32_e32 v40, 1, v204
	v_ashrrev_i32_e32 v42, 1, v205
	v_ashrrev_i32_e32 v44, 1, v206
	v_ashrrev_i32_e32 v46, 1, v207
	v_ashrrev_i32_e32 v33, 31, v32
	v_ashrrev_i32_e32 v35, 31, v34
	v_ashrrev_i32_e32 v37, 31, v36
	v_ashrrev_i32_e32 v39, 31, v38
	v_ashrrev_i32_e32 v41, 31, v40
	v_ashrrev_i32_e32 v43, 31, v42
	v_ashrrev_i32_e32 v45, 31, v44
	v_lshlrev_b64 v[4:5], 11, v[34:35]
	v_lshl_add_u64 v[4:5], s[2:3], 0, v[4:5]
	v_lshl_add_u64 v[4:5], v[4:5], 0, v[148:149]
	v_mov_b32_e32 v2, v172
	v_ashrrev_i32_e32 v47, 31, v46
	v_lshlrev_b32_e32 v52, 4, v2
	v_lshlrev_b64 v[2:3], 11, v[32:33]
	v_lshl_add_u64 v[2:3], s[2:3], 0, v[2:3]
	v_readfirstlane_b32 s0, v52
	v_add_u32_e32 v6, 0x1000, v52
	v_lshl_add_u64 v[2:3], v[2:3], 0, v[148:149]
	s_mov_b32 m0, s0
	v_readfirstlane_b32 s0, v6
	v_lshlrev_b64 v[6:7], 11, v[36:37]
	v_add_u32_e32 v8, 0x2000, v52
	global_load_lds_dwordx4 v[2:3], off
	s_mov_b32 m0, s0
	v_lshl_add_u64 v[6:7], s[2:3], 0, v[6:7]
	v_readfirstlane_b32 s0, v8
	v_lshlrev_b64 v[8:9], 11, v[38:39]
	v_add_u32_e32 v10, 0x3000, v52
	global_load_lds_dwordx4 v[4:5], off
	v_lshl_add_u64 v[6:7], v[6:7], 0, v[148:149]
	s_mov_b32 m0, s0
	v_lshl_add_u64 v[8:9], s[2:3], 0, v[8:9]
	v_readfirstlane_b32 s0, v10
	v_lshlrev_b64 v[10:11], 11, v[40:41]
	v_add_u32_e32 v12, 0x4000, v52
	global_load_lds_dwordx4 v[6:7], off
	v_lshl_add_u64 v[8:9], v[8:9], 0, v[148:149]
	s_mov_b32 m0, s0
	v_lshl_add_u64 v[10:11], s[2:3], 0, v[10:11]
	v_readfirstlane_b32 s0, v12
	v_lshlrev_b64 v[12:13], 11, v[42:43]
	v_add_u32_e32 v14, 0x5000, v52
	global_load_lds_dwordx4 v[8:9], off
	v_lshl_add_u64 v[10:11], v[10:11], 0, v[148:149]
	s_mov_b32 m0, s0
	v_lshl_add_u64 v[12:13], s[2:3], 0, v[12:13]
	v_readfirstlane_b32 s0, v14
	v_lshlrev_b64 v[14:15], 11, v[44:45]
	v_add_u32_e32 v16, 0x6000, v52
	global_load_lds_dwordx4 v[10:11], off
	v_lshl_add_u64 v[12:13], v[12:13], 0, v[148:149]
	s_mov_b32 m0, s0
	v_lshl_add_u64 v[14:15], s[2:3], 0, v[14:15]
	v_readfirstlane_b32 s0, v16
	v_lshlrev_b64 v[16:17], 11, v[46:47]
	v_add_u32_e32 v18, 0x7000, v52
	global_load_lds_dwordx4 v[12:13], off
	v_lshl_add_u64 v[14:15], v[14:15], 0, v[148:149]
	s_mov_b32 m0, s0
	v_lshl_add_u64 v[16:17], s[2:3], 0, v[16:17]
	v_readfirstlane_b32 s0, v18
	v_add_u32_e32 v20, 0x8000, v52
	global_load_lds_dwordx4 v[14:15], off
	v_lshl_add_u64 v[16:17], v[16:17], 0, v[148:149]
	s_mov_b32 m0, s0
	v_readfirstlane_b32 s0, v20
	v_add_u32_e32 v22, 0x9000, v52
	global_load_lds_dwordx4 v[16:17], off
	v_lshl_add_u64 v[18:19], v[28:29], 0, v[48:49]
	s_mov_b32 m0, s0
	v_readfirstlane_b32 s0, v22
	v_add_u32_e32 v25, 0xa000, v52
	global_load_lds_dwordx4 v[18:19], off
	v_lshl_add_u64 v[20:21], v[30:31], 0, v[48:49]
	s_mov_b32 m0, s0
	v_readfirstlane_b32 s0, v25
	v_add_u32_e32 v25, 0xb000, v52
	global_load_lds_dwordx4 v[20:21], off
	v_lshl_add_u64 v[22:23], v[28:29], 0, v[50:51]
	s_mov_b32 m0, s0
	v_readfirstlane_b32 s0, v25
	v_add_u32_e32 v25, 0xc000, v52
	global_load_lds_dwordx4 v[22:23], off
	s_mov_b32 m0, s0
	v_readfirstlane_b32 s0, v25
	global_load_lds_dwordx4 v[56:57], off
	v_lshl_add_u64 v[2:3], v[2:3], 0, s[92:93]
	s_mov_b32 m0, s0
	s_nop 0
	global_load_lds_dwordx4 v[2:3], off
	v_lshl_add_u64 v[2:3], v[4:5], 0, s[92:93]
	v_add_u32_e32 v4, 0xd000, v52
	s_nop 0
	v_readfirstlane_b32 s0, v4
	v_add_u32_e32 v4, 0xe000, v52
	s_mov_b32 m0, s0
	v_readfirstlane_b32 s0, v4
	v_add_u32_e32 v4, 0xf000, v52
	global_load_lds_dwordx4 v[2:3], off
	v_lshl_add_u64 v[2:3], v[6:7], 0, s[92:93]
	s_mov_b32 m0, s0
	v_readfirstlane_b32 s0, v4
	v_add_u32_e32 v4, 0x10000, v52
	global_load_lds_dwordx4 v[2:3], off
	v_lshl_add_u64 v[2:3], v[8:9], 0, s[92:93]
	s_mov_b32 m0, s0
	v_readfirstlane_b32 s0, v4
	v_add_u32_e32 v4, 0x11000, v52
	global_load_lds_dwordx4 v[2:3], off
	v_lshl_add_u64 v[2:3], v[10:11], 0, s[92:93]
	s_mov_b32 m0, s0
	v_readfirstlane_b32 s0, v4
	v_add_u32_e32 v4, 0x12000, v52
	global_load_lds_dwordx4 v[2:3], off
	v_lshl_add_u64 v[2:3], v[12:13], 0, s[92:93]
	s_mov_b32 m0, s0
	v_readfirstlane_b32 s0, v4
	v_add_u32_e32 v4, 0x13000, v52
	global_load_lds_dwordx4 v[2:3], off
	v_lshl_add_u64 v[2:3], v[14:15], 0, s[92:93]
	s_mov_b32 m0, s0
	v_readfirstlane_b32 s0, v4
	v_add_u32_e32 v4, 0x14000, v52
	global_load_lds_dwordx4 v[2:3], off
	v_lshl_add_u64 v[2:3], v[16:17], 0, s[92:93]
	s_mov_b32 m0, s0
	v_readfirstlane_b32 s0, v4
	v_add_u32_e32 v4, 0x15000, v52
	global_load_lds_dwordx4 v[2:3], off
	v_lshl_add_u64 v[2:3], v[18:19], 0, s[92:93]
	s_mov_b32 m0, s0
	v_readfirstlane_b32 s0, v4
	v_add_u32_e32 v4, 0x16000, v52
	global_load_lds_dwordx4 v[2:3], off
	v_lshl_add_u64 v[2:3], v[20:21], 0, s[92:93]
	s_mov_b32 m0, s0
	v_readfirstlane_b32 s0, v4
	v_add_u32_e32 v4, 0x17000, v52
	global_load_lds_dwordx4 v[2:3], off
	v_lshl_add_u64 v[2:3], v[22:23], 0, s[92:93]
	s_mov_b32 m0, s0
	v_readfirstlane_b32 s0, v4
	global_load_lds_dwordx4 v[2:3], off
	v_lshl_add_u64 v[2:3], v[56:57], 0, s[92:93]
	s_mov_b32 m0, s0
	v_readlane_b32 s0, v254, 32
	global_load_lds_dwordx4 v[2:3], off
	v_lshl_add_u64 v[52:53], s[2:3], 0, v[148:149]
	v_lshlrev_b32_e32 v148, 4, v1
	v_readlane_b32 s1, v254, 33
	v_lshlrev_b32_e32 v56, 1, v0
	s_nop 0
	v_lshl_add_u64 v[54:55], s[0:1], 0, v[148:149]
	s_branch .LBB0_569
